# masked attention units remapped: a CU's 3 window units share one (batch, kv head, q block); its 3 nbr units are consecutive q blocks of one head (K/V reuse from L2)
# speedup vs baseline: 1.0013x; 1.0013x over previous
; __device__ __forceinline__ unsigned pk_bf16(float lo, float hi) { unsigned r; asm volatile("v_cvt_pk_bf16_f32 %0, %1, %2" : "=v"(r) : "v"(lo), "v"(hi)); return r; }
; __device__ __forceinline__ float halfsum(float v) { auto rr = __builtin_amdgcn_permlane32_swap(__float_as_uint(v), __float_as_uint(v), false, false); return __uint_as_float(rr[0]) + __uint_as_float(rr[1]); }
; __device__ __forceinline__ void attn_unit(int uv, const float* sink_l, const bf16_t* P, bf16_t* Y, ATT_LAS unsigned char* lds, const float* rpb_l, const float* qn_l, const float* kn_l) {
;     ...
;     lsum = halfsum(lsum);
;     lsum += __builtin_amdgcn_exp2f(a.sink - m);
;     const float inv = 1.0f / lsum;
;     bf16_t* yr = Y + ((size_t)(qrow >> 8) * 16 + (a.qcol >> 6)) * 16384 + (qrow & 255) * 64 + 4 * hi;
; #pragma unroll
;     for (int g = 0; g < 4; ++g) {
;         u32x2 w0, w1;
;         w0.x = pk_bf16(o0[4 * g] * inv, o0[4 * g + 1] * inv); w0.y = pk_bf16(o0[4 * g + 2] * inv, o0[4 * g + 3] * inv);
;         w1.x = pk_bf16(o1[4 * g] * inv, o1[4 * g + 1] * inv); w1.y = pk_bf16(o1[4 * g + 2] * inv, o1[4 * g + 3] * inv);
;         *(u32x2*)(yr + 8 * g) = w0; *(u32x2*)(yr + 32 + 8 * g) = w1;
;     }
; __global__ void __launch_bounds__(NTHREADS, 2) fwd_megakernel(Args A) {
;     ...
;           for (int v = bx; v < nunits + ATT_EXTRA; v += G) att::attn_unit(v < nunits ? v : v - nunits, sink_l, P, Y, lds, rpb_l, qn_l, kn_l); }
.LBB0_536:
	v_sub_f32_e32 v33, v217, v202
	v_exp_f32_e32 v33, v33
	v_mov_b32_e32 v32, v124
	s_nop 1
	v_permlane32_swap_b32_e32 v124, v32
	v_add_f32_e32 v32, v124, v32
	v_add_f32_e32 v32, v33, v32
	v_div_scale_f32 v33, s[0:1], v32, v32, 1.0
	v_rcp_f32_e32 v34, v33
	v_readlane_b32 s0, v255, 33
	v_readlane_b32 s1, v255, 34
	s_ashr_i32 s0, s0, 6
	v_fma_f32 v35, -v33, v34, 1.0
	v_fmac_f32_e32 v34, v35, v34
	v_div_scale_f32 v35, vcc, 1.0, v32, 1.0
	v_mul_f32_e32 v36, v35, v34
	v_fma_f32 v37, -v33, v36, v35
	v_fmac_f32_e32 v36, v37, v34
	v_fma_f32 v33, -v33, v36, v35
	v_div_fmas_f32 v33, v33, v34, v36
	v_div_fixup_f32 v34, v33, v32, 1.0
	v_ashrrev_i32_e32 v32, 8, v218
	v_ashrrev_i32_e32 v33, 31, v32
	v_readlane_b32 s2, v255, 26
	s_ashr_i32 s1, s0, 31
	v_lshlrev_b64 v[32:33], 19, v[32:33]
	v_readlane_b32 s3, v255, 27
	s_lshl_b64 s[0:1], s[0:1], 15
	v_lshlrev_b32_e32 v35, 7, v218
	v_lshl_add_u64 v[32:33], s[2:3], 0, v[32:33]
	v_mul_f32_e32 v0, v0, v34
	v_mul_f32_e32 v1, v1, v34
	v_lshl_add_u64 v[32:33], v[32:33], 0, s[0:1]
	v_and_b32_e32 v196, 0x7f80, v35
	v_cvt_pk_bf16_f32 v0, v0, v1
	v_mul_f32_e32 v1, v2, v34
	v_mul_f32_e32 v2, v3, v34
	v_lshl_add_u64 v[32:33], v[32:33], 0, v[196:197]
	v_lshlrev_b32_e32 v196, 1, v219
	v_cvt_pk_bf16_f32 v1, v1, v2
	v_mul_f32_e32 v2, v16, v34
	v_mul_f32_e32 v3, v17, v34
	v_lshl_add_u64 v[32:33], v[32:33], 0, v[196:197]
	v_cvt_pk_bf16_f32 v2, v2, v3
	v_mul_f32_e32 v3, v18, v34
	v_mul_f32_e32 v16, v19, v34
	v_cvt_pk_bf16_f32 v3, v3, v16
	global_store_dwordx2 v[32:33], v[0:1], off
	global_store_dwordx2 v[32:33], v[2:3], off offset:64
	v_mul_f32_e32 v0, v4, v34
	v_mul_f32_e32 v1, v5, v34
	v_cvt_pk_bf16_f32 v0, v0, v1
	v_mul_f32_e32 v1, v6, v34
	v_mul_f32_e32 v2, v7, v34
	v_cvt_pk_bf16_f32 v1, v1, v2
	v_mul_f32_e32 v2, v20, v34
	v_mul_f32_e32 v3, v21, v34
	v_cvt_pk_bf16_f32 v2, v2, v3
	v_mul_f32_e32 v3, v22, v34
	v_mul_f32_e32 v4, v23, v34
	v_cvt_pk_bf16_f32 v3, v3, v4
	global_store_dwordx2 v[32:33], v[0:1], off offset:16
	global_store_dwordx2 v[32:33], v[2:3], off offset:80
	v_mul_f32_e32 v0, v8, v34
	v_mul_f32_e32 v1, v9, v34
	v_cvt_pk_bf16_f32 v0, v0, v1
	v_mul_f32_e32 v1, v10, v34
	v_mul_f32_e32 v2, v11, v34
	v_cvt_pk_bf16_f32 v1, v1, v2
	v_mul_f32_e32 v2, v24, v34
	v_mul_f32_e32 v3, v25, v34
	v_cvt_pk_bf16_f32 v2, v2, v3
	v_mul_f32_e32 v3, v26, v34
	v_mul_f32_e32 v4, v27, v34
	v_cvt_pk_bf16_f32 v3, v3, v4
	global_store_dwordx2 v[32:33], v[0:1], off offset:32
	global_store_dwordx2 v[32:33], v[2:3], off offset:96
	v_mul_f32_e32 v0, v12, v34
	v_mul_f32_e32 v1, v13, v34
	v_cvt_pk_bf16_f32 v0, v0, v1
	v_mul_f32_e32 v1, v14, v34
	v_mul_f32_e32 v2, v15, v34
	v_cvt_pk_bf16_f32 v1, v1, v2
	v_mul_f32_e32 v2, v28, v34
	v_mul_f32_e32 v3, v29, v34
	v_readlane_b32 s74, v255, 60
	s_nop 0
	s_add_i32 s74, s74, s70
	v_cvt_pk_bf16_f32 v2, v2, v3
	v_mul_f32_e32 v3, v30, v34
	s_cmp_ge_i32 s74, s36
	v_mul_f32_e32 v4, v31, v34
	v_cvt_pk_bf16_f32 v3, v3, v4
	global_store_dwordx2 v[32:33], v[0:1], off offset:48
	global_store_dwordx2 v[32:33], v[2:3], off offset:112
	s_cbranch_scc1 .LBB0_700
.LBB0_537:
	v_writelane_b32 v255, s74, 60
	s_cmpk_lt_u32 s74, 0x200
	s_cbranch_scc1 .Lperm_done
	s_cmpk_gt_u32 s74, 0x7ff
	s_cbranch_scc1 .Lperm_done
	s_cmpk_gt_u32 s74, 0x4ff
	s_cbranch_scc1 .Lperm_nbr
	s_sub_u32 s0, s74, 0x200
	s_lshr_b32 s1, s0, 8
	s_and_b32 s0, s0, 0xff
	s_bfe_u32 vcc_lo, s0, 0x10005
	s_mul_i32 vcc_lo, vcc_lo, 3
	s_add_u32 s1, s1, vcc_lo
	s_lshl_b32 s1, s1, 5
	s_lshr_b32 vcc_lo, s0, 6
	s_mul_i32 vcc_lo, vcc_lo, 0xc0
	s_and_b32 s0, s0, 31
	s_add_u32 s0, s0, s1
	s_add_u32 s0, s0, vcc_lo
	s_add_u32 s74, s0, 0x200
	s_branch .Lperm_done
.Lperm_nbr:
	s_sub_u32 s0, s74, 0x500
	s_lshr_b32 s1, s0, 8
	s_and_b32 s0, s0, 0xff
	s_mul_i32 s0, s0, 3
	s_add_u32 s0, s0, s1
	s_add_u32 s74, s0, 0x500
